# RMSNorm row loops: sum of squares via DPP row reduce + readlane combine
# baseline (speedup 1.0000x reference)
.LBB0_180:
	s_or_b64 exec, exec, s[18:19]
	v_lshlrev_b32_e32 v80, 16, v6
	v_and_b32_e32 v81, 0xffff0000, v6
	v_lshlrev_b32_e32 v76, 16, v7
	v_and_b32_e32 v77, 0xffff0000, v7
	v_pk_mul_f32 v[6:7], v[80:81], v[80:81]
	v_pk_mul_f32 v[78:79], v[76:77], v[76:77]
	v_add_f32_e32 v6, v6, v7
	v_lshlrev_b32_e32 v74, 16, v8
	v_and_b32_e32 v75, 0xffff0000, v8
	v_add_f32_e32 v6, v78, v6
	v_lshlrev_b32_e32 v70, 16, v9
	v_and_b32_e32 v71, 0xffff0000, v9
	v_pk_mul_f32 v[8:9], v[74:75], v[74:75]
	v_add_f32_e32 v6, v79, v6
	v_add_f32_e32 v6, v8, v6
	v_pk_mul_f32 v[72:73], v[70:71], v[70:71]
	v_add_f32_e32 v6, v9, v6
	v_lshlrev_b32_e32 v92, 16, v2
	v_and_b32_e32 v93, 0xffff0000, v2
	v_add_f32_e32 v6, v72, v6
	v_lshlrev_b32_e32 v88, 16, v3
	v_and_b32_e32 v89, 0xffff0000, v3
	v_pk_mul_f32 v[2:3], v[92:93], v[92:93]
	v_add_f32_e32 v6, v73, v6
	v_add_f32_e32 v2, v2, v6
	v_pk_mul_f32 v[90:91], v[88:89], v[88:89]
	v_add_f32_e32 v2, v3, v2
	v_lshlrev_b32_e32 v86, 16, v4
	v_and_b32_e32 v87, 0xffff0000, v4
	v_add_f32_e32 v2, v90, v2
	v_lshlrev_b32_e32 v82, 16, v5
	v_and_b32_e32 v83, 0xffff0000, v5
	v_pk_mul_f32 v[4:5], v[86:87], v[86:87]
	v_add_f32_e32 v2, v91, v2
	v_add_f32_e32 v2, v4, v2
	v_pk_mul_f32 v[84:85], v[82:83], v[82:83]
	v_add_f32_e32 v2, v5, v2
	v_add_f32_e32 v2, v84, v2
	v_add_f32_e32 v2, v85, v2
	s_nop 0
	s_and_b64 s[4:5], exec, s[4:5]
	v_lshl_add_u64 v[6:7], v[38:39], 0, v[36:37]
	s_or_b64 s[14:15], s[4:5], s[14:15]
	s_mov_b32 s4, 0x15200000
	s_nop 0
	s_nop 0
	s_nop 0
	v_mov_b32_e32 v62, v63
	s_nop 0
	s_nop 0
	s_nop 0
	s_nop 0
	s_nop 0
	s_nop 0
	s_nop 0
	s_nop 0
	s_nop 0
	s_nop 0
	s_nop 0
	s_nop 0
	s_nop 0
	s_nop 1
	v_add_f32_dpp v3, v2, v2 quad_perm:[1,0,3,2] row_mask:0xf bank_mask:0xf
	s_nop 1
	v_add_f32_dpp v3, v3, v3 quad_perm:[2,3,0,1] row_mask:0xf bank_mask:0xf
	s_nop 1
	v_add_f32_dpp v3, v3, v3 row_half_mirror row_mask:0xf bank_mask:0xf
	s_nop 1
	v_add_f32_dpp v3, v3, v3 row_mirror row_mask:0xf bank_mask:0xf
	s_nop 1
	v_readlane_b32 s60, v3, 0
	v_readlane_b32 s61, v3, 16
	v_readlane_b32 s62, v3, 32
	v_readlane_b32 s63, v3, 48
	s_nop 2
	v_mov_b32_e32 v2, s60
	v_add_f32_e32 v2, s61, v2
	v_add_f32_e32 v2, s62, v2
	v_add_f32_e32 v2, s63, v2
	v_fmamk_f32 v2, v2, 0x3a800000, v179
	v_mul_f32_e32 v3, 0x4b800000, v2
	v_cmp_gt_f32_e32 vcc, s71, v2
	s_nop 1
	v_cndmask_b32_e32 v2, v2, v3, vcc
	v_rsq_f32_e32 v2, v2
	s_nop 0
	v_mul_f32_e32 v3, 0x45800000, v2
	v_cndmask_b32_e32 v8, v2, v3, vcc
	v_pk_mul_f32 v[2:3], v[8:9], v[80:81] op_sel_hi:[0,1]
	v_pk_mul_f32 v[4:5], v[8:9], v[76:77] op_sel_hi:[0,1]
	v_pk_mul_f32 v[72:73], v[8:9], v[74:75] op_sel_hi:[0,1]
	v_pk_mul_f32 v[70:71], v[8:9], v[70:71] op_sel_hi:[0,1]
	s_waitcnt vmcnt(3)
	v_pk_fma_f32 v[2:3], v[58:59], v[2:3], v[22:23]
	v_pk_fma_f32 v[4:5], v[56:57], v[4:5], v[24:25]
	s_waitcnt vmcnt(2)
	v_pk_fma_f32 v[72:73], v[54:55], v[72:73], v[10:11]
	v_pk_fma_f32 v[70:71], v[52:53], v[70:71], v[12:13]
	v_add_co_u32_e32 v6, vcc, s4, v6
	v_cvt_pk_bf16_f32 v2, v2, v3
	v_cvt_pk_bf16_f32 v3, v4, v5
	v_cvt_pk_bf16_f32 v4, v72, v73
	v_cvt_pk_bf16_f32 v5, v70, v71
	v_addc_co_u32_e32 v7, vcc, 0, v7, vcc
	global_store_dwordx4 v[6:7], v[2:5], off
	v_pk_mul_f32 v[70:71], v[8:9], v[86:87] op_sel_hi:[0,1]
	s_waitcnt vmcnt(1)
	v_pk_fma_f32 v[70:71], v[46:47], v[70:71], v[30:31]
	v_pk_mul_f32 v[2:3], v[8:9], v[92:93] op_sel_hi:[0,1]
	v_pk_mul_f32 v[4:5], v[8:9], v[88:89] op_sel_hi:[0,1]
	v_pk_mul_f32 v[8:9], v[8:9], v[82:83] op_sel_hi:[0,1]
	v_pk_fma_f32 v[2:3], v[50:51], v[2:3], v[26:27]
	v_pk_fma_f32 v[4:5], v[48:49], v[4:5], v[28:29]
	v_pk_fma_f32 v[8:9], v[60:61], v[8:9], v[32:33]
	v_cvt_pk_bf16_f32 v2, v2, v3
	v_cvt_pk_bf16_f32 v3, v4, v5
	v_cvt_pk_bf16_f32 v4, v70, v71
	v_cvt_pk_bf16_f32 v5, v8, v9
	s_mov_b64 s[4:5], 0x800
	global_store_dwordx4 v[6:7], v[2:5], off offset:1024
	v_lshl_add_u64 v[38:39], v[38:39], 0, s[4:5]
	s_mov_b64 s[4:5], 0x1000
	v_mov_b64_e32 v[6:7], v[18:19]
	v_mov_b64_e32 v[2:3], v[14:15]
	v_lshl_add_u64 v[34:35], v[34:35], 0, s[4:5]
	v_mov_b64_e32 v[8:9], v[20:21]
	v_mov_b64_e32 v[4:5], v[16:17]
	s_andn2_b64 exec, exec, s[14:15]
	s_cbranch_execz .LBB0_185

.LBB0_189:
	s_or_b64 exec, exec, s[2:3]
	v_pk_mul_f32 v[100:101], v[72:73], v[72:73]
	v_pk_mul_f32 v[102:103], v[68:69], v[68:69]
	v_pk_mul_f32 v[96:97], v[74:75], v[74:75]
	v_pk_mul_f32 v[98:99], v[70:71], v[70:71]
	v_mov_b32_e32 v104, v100
	v_mov_b32_e32 v105, v102
	v_mov_b32_e32 v102, v101
	v_pk_add_f32 v[100:101], v[104:105], v[102:103]
	v_mov_b32_e32 v102, v96
	v_mov_b32_e32 v103, v98
	v_pk_mul_f32 v[92:93], v[60:61], v[60:61]
	v_pk_mul_f32 v[94:95], v[64:65], v[64:65]
	v_pk_add_f32 v[100:101], v[102:103], v[100:101]
	v_mov_b32_e32 v98, v97
	v_pk_mul_f32 v[88:89], v[62:63], v[62:63]
	v_pk_mul_f32 v[90:91], v[66:67], v[66:67]
	v_pk_add_f32 v[96:97], v[98:99], v[100:101]
	v_mov_b32_e32 v98, v92
	v_mov_b32_e32 v99, v94
	v_mov_b32_e32 v94, v93
	v_pk_add_f32 v[92:93], v[98:99], v[94:95]
	v_mov_b32_e32 v94, v88
	v_mov_b32_e32 v95, v90
	v_pk_add_f32 v[92:93], v[94:95], v[92:93]
	v_mov_b32_e32 v90, v89
	v_pk_add_f32 v[88:89], v[90:91], v[92:93]
	v_add_f32_e32 v41, v96, v97
	v_add_f32_e32 v41, v89, v41
	v_add_f32_e32 v41, v88, v41
	s_nop 0
	s_and_b64 s[2:3], exec, vcc
	s_or_b64 s[12:13], s[2:3], s[12:13]
	s_mov_b64 s[2:3], 0x800
	s_nop 0
	s_nop 0
	s_nop 0
	s_nop 0
	s_nop 0
	s_nop 0
	s_nop 0
	s_nop 0
	s_nop 0
	s_nop 0
	s_nop 0
	s_nop 0
	s_nop 0
	s_nop 0
	s_nop 0
	s_nop 0
	s_nop 1
	v_add_f32_dpp v43, v41, v41 quad_perm:[1,0,3,2] row_mask:0xf bank_mask:0xf
	s_nop 1
	v_add_f32_dpp v43, v43, v43 quad_perm:[2,3,0,1] row_mask:0xf bank_mask:0xf
	s_nop 1
	v_add_f32_dpp v43, v43, v43 row_half_mirror row_mask:0xf bank_mask:0xf
	s_nop 1
	v_add_f32_dpp v43, v43, v43 row_mirror row_mask:0xf bank_mask:0xf
	s_nop 1
	v_readlane_b32 s60, v43, 0
	v_readlane_b32 s61, v43, 16
	v_readlane_b32 s62, v43, 32
	v_readlane_b32 s63, v43, 48
	s_nop 2
	v_mov_b32_e32 v41, s60
	v_add_f32_e32 v41, s61, v41
	v_add_f32_e32 v41, s62, v41
	v_add_f32_e32 v41, s63, v41
	v_fmamk_f32 v41, v41, 0x3a800000, v179
	v_mul_f32_e32 v43, 0x4b800000, v41
	v_cmp_gt_f32_e64 s[4:5], s71, v41
	s_nop 1
	v_cndmask_b32_e64 v41, v41, v43, s[4:5]
	v_rsq_f32_e32 v41, v41
	s_nop 0
	v_mul_f32_e32 v43, 0x45800000, v41
	v_cndmask_b32_e64 v80, v41, v43, s[4:5]
	v_pk_mul_f32 v[72:73], v[72:73], v[80:81] op_sel_hi:[1,0]
	v_pk_mul_f32 v[74:75], v[74:75], v[80:81] op_sel_hi:[1,0]
	v_pk_mul_f32 v[68:69], v[68:69], v[80:81] op_sel_hi:[1,0]
	v_pk_mul_f32 v[70:71], v[70:71], v[80:81] op_sel_hi:[1,0]
	v_pk_mul_f32 v[64:65], v[64:65], v[80:81] op_sel_hi:[1,0]
	v_pk_mul_f32 v[66:67], v[66:67], v[80:81] op_sel_hi:[1,0]
	v_pk_mul_f32 v[60:61], v[60:61], v[80:81] op_sel_hi:[1,0]
	v_pk_mul_f32 v[62:63], v[62:63], v[80:81] op_sel_hi:[1,0]
	v_pk_fma_f32 v[74:75], v[36:37], v[74:75], v[20:21]
	v_pk_fma_f32 v[72:73], v[34:35], v[72:73], v[18:19]
	v_pk_fma_f32 v[70:71], v[54:55], v[70:71], v[24:25]
	v_pk_fma_f32 v[68:69], v[52:53], v[68:69], v[22:23]
	v_pk_fma_f32 v[66:67], v[58:59], v[66:67], v[28:29]
	v_pk_fma_f32 v[64:65], v[56:57], v[64:65], v[26:27]
	s_waitcnt vmcnt(0)
	v_pk_fma_f32 v[62:63], v[78:79], v[62:63], v[32:33]
	v_pk_fma_f32 v[60:61], v[76:77], v[60:61], v[30:31]
	v_cvt_pk_bf16_f32 v72, v72, v73
	v_cvt_pk_bf16_f32 v73, v74, v75
	v_cvt_pk_bf16_f32 v68, v68, v69
	v_cvt_pk_bf16_f32 v69, v70, v71
	v_cvt_pk_bf16_f32 v64, v64, v65
	v_cvt_pk_bf16_f32 v65, v66, v67
	v_cvt_pk_bf16_f32 v60, v60, v61
	v_cvt_pk_bf16_f32 v61, v62, v63
	global_store_dwordx2 v[48:49], v[72:73], off
	global_store_dwordx2 v[48:49], v[68:69], off offset:512
	global_store_dwordx2 v[48:49], v[64:65], off offset:1024
	global_store_dwordx2 v[48:49], v[60:61], off offset:1536
	v_lshl_add_u64 v[48:49], v[48:49], 0, s[2:3]
	s_mov_b64 s[2:3], 0x1000
	v_lshl_add_u64 v[50:51], v[50:51], 0, s[2:3]
	v_mov_b32_e32 v80, v81
	v_mov_b32_e32 v72, v2
	v_mov_b32_e32 v73, v3
	v_mov_b32_e32 v74, v4
	v_mov_b32_e32 v75, v5
	v_mov_b32_e32 v68, v6
	v_mov_b32_e32 v69, v7
	v_mov_b32_e32 v70, v8
	v_mov_b32_e32 v71, v9
	v_mov_b32_e32 v64, v10
	v_mov_b32_e32 v65, v11
	v_mov_b32_e32 v66, v12
	v_mov_b32_e32 v67, v13
	v_mov_b32_e32 v60, v14
	v_mov_b32_e32 v61, v15
	v_mov_b32_e32 v62, v16
	v_mov_b32_e32 v63, v17
	s_andn2_b64 exec, exec, s[12:13]
	s_cbranch_execz .LBB0_194

.LBB0_460:
	s_or_b64 exec, exec, s[10:11]
	v_lshlrev_b32_e32 v84, 16, v22
	v_and_b32_e32 v85, 0xffff0000, v22
	v_lshlrev_b32_e32 v80, 16, v23
	v_and_b32_e32 v81, 0xffff0000, v23
	v_pk_mul_f32 v[22:23], v[84:85], v[84:85]
	v_pk_mul_f32 v[82:83], v[80:81], v[80:81]
	v_add_f32_e32 v22, v22, v23
	v_lshlrev_b32_e32 v78, 16, v24
	v_and_b32_e32 v79, 0xffff0000, v24
	v_add_f32_e32 v22, v82, v22
	v_lshlrev_b32_e32 v74, 16, v25
	v_and_b32_e32 v75, 0xffff0000, v25
	v_pk_mul_f32 v[24:25], v[78:79], v[78:79]
	v_add_f32_e32 v22, v83, v22
	v_add_f32_e32 v22, v24, v22
	v_pk_mul_f32 v[76:77], v[74:75], v[74:75]
	v_add_f32_e32 v22, v25, v22
	v_lshlrev_b32_e32 v96, 16, v10
	v_and_b32_e32 v97, 0xffff0000, v10
	v_add_f32_e32 v22, v76, v22
	v_lshlrev_b32_e32 v92, 16, v11
	v_and_b32_e32 v93, 0xffff0000, v11
	v_pk_mul_f32 v[10:11], v[96:97], v[96:97]
	v_add_f32_e32 v22, v77, v22
	v_add_f32_e32 v10, v10, v22
	v_pk_mul_f32 v[94:95], v[92:93], v[92:93]
	v_add_f32_e32 v10, v11, v10
	v_lshlrev_b32_e32 v90, 16, v12
	v_and_b32_e32 v91, 0xffff0000, v12
	v_add_f32_e32 v10, v94, v10
	v_lshlrev_b32_e32 v86, 16, v13
	v_and_b32_e32 v87, 0xffff0000, v13
	v_pk_mul_f32 v[12:13], v[90:91], v[90:91]
	v_add_f32_e32 v10, v95, v10
	v_add_f32_e32 v10, v12, v10
	v_pk_mul_f32 v[88:89], v[86:87], v[86:87]
	v_add_f32_e32 v10, v13, v10
	v_add_f32_e32 v10, v88, v10
	v_add_f32_e32 v10, v89, v10
	s_nop 0
	s_and_b64 s[4:5], exec, s[4:5]
	s_or_b64 s[8:9], s[4:5], s[8:9]
	v_lshl_add_u64 v[72:73], v[50:51], 0, v[36:37]
	s_mov_b32 s4, 0x15200000
	s_nop 0
	s_nop 0
	s_nop 0
	v_mov_b32_e32 v64, v65
	s_nop 0
	s_nop 0
	s_nop 0
	s_nop 0
	s_nop 0
	s_nop 0
	s_nop 0
	s_nop 0
	s_nop 0
	s_nop 0
	s_nop 0
	s_nop 0
	s_nop 0
	s_nop 1
	v_add_f32_dpp v11, v10, v10 quad_perm:[1,0,3,2] row_mask:0xf bank_mask:0xf
	s_nop 1
	v_add_f32_dpp v11, v11, v11 quad_perm:[2,3,0,1] row_mask:0xf bank_mask:0xf
	s_nop 1
	v_add_f32_dpp v11, v11, v11 row_half_mirror row_mask:0xf bank_mask:0xf
	s_nop 1
	v_add_f32_dpp v11, v11, v11 row_mirror row_mask:0xf bank_mask:0xf
	s_nop 1
	v_readlane_b32 s60, v11, 0
	v_readlane_b32 s61, v11, 16
	v_readlane_b32 s62, v11, 32
	v_readlane_b32 s63, v11, 48
	s_nop 2
	v_mov_b32_e32 v10, s60
	v_add_f32_e32 v10, s61, v10
	v_add_f32_e32 v10, s62, v10
	v_add_f32_e32 v10, s63, v10
	v_fmamk_f32 v10, v10, 0x3a800000, v179
	v_cmp_gt_f32_e32 vcc, s71, v10
	v_mul_f32_e32 v11, 0x4b800000, v10
	s_nop 0
	v_cndmask_b32_e32 v10, v10, v11, vcc
	v_rsq_f32_e32 v10, v10
	s_nop 0
	v_mul_f32_e32 v11, 0x45800000, v10
	v_cndmask_b32_e32 v22, v10, v11, vcc
	v_pk_mul_f32 v[10:11], v[22:23], v[84:85] op_sel_hi:[0,1]
	v_pk_mul_f32 v[12:13], v[22:23], v[80:81] op_sel_hi:[0,1]
	v_pk_mul_f32 v[24:25], v[22:23], v[78:79] op_sel_hi:[0,1]
	v_pk_fma_f32 v[10:11], v[38:39], v[10:11], v[6:7]
	v_pk_fma_f32 v[12:13], v[40:41], v[12:13], v[8:9]
	v_pk_fma_f32 v[24:25], v[42:43], v[24:25], v[2:3]
	v_pk_mul_f32 v[74:75], v[22:23], v[74:75] op_sel_hi:[0,1]
	v_pk_fma_f32 v[74:75], v[44:45], v[74:75], v[4:5]
	v_cvt_pk_bf16_f32 v10, v10, v11
	v_cvt_pk_bf16_f32 v11, v12, v13
	v_cvt_pk_bf16_f32 v12, v24, v25
	v_add_co_u32_e32 v24, vcc, s4, v72
	v_cvt_pk_bf16_f32 v13, v74, v75
	s_nop 0
	v_addc_co_u32_e32 v25, vcc, 0, v73, vcc
	global_store_dwordx4 v[24:25], v[10:13], off
	v_pk_mul_f32 v[72:73], v[22:23], v[90:91] op_sel_hi:[0,1]
	s_waitcnt vmcnt(1)
	v_pk_fma_f32 v[72:73], v[60:61], v[72:73], v[30:31]
	v_pk_mul_f32 v[10:11], v[22:23], v[96:97] op_sel_hi:[0,1]
	v_pk_mul_f32 v[12:13], v[22:23], v[92:93] op_sel_hi:[0,1]
	v_pk_mul_f32 v[22:23], v[22:23], v[86:87] op_sel_hi:[0,1]
	v_pk_fma_f32 v[10:11], v[56:57], v[10:11], v[26:27]
	v_pk_fma_f32 v[12:13], v[58:59], v[12:13], v[28:29]
	v_pk_fma_f32 v[22:23], v[62:63], v[22:23], v[32:33]
	v_cvt_pk_bf16_f32 v10, v10, v11
	v_cvt_pk_bf16_f32 v11, v12, v13
	v_cvt_pk_bf16_f32 v12, v72, v73
	v_cvt_pk_bf16_f32 v13, v22, v23
	s_mov_b64 s[4:5], 0x800
	global_store_dwordx4 v[24:25], v[10:13], off offset:1024
	v_lshl_add_u64 v[50:51], v[50:51], 0, s[4:5]
	s_mov_b64 s[4:5], 0x1000
	v_mov_b64_e32 v[24:25], v[20:21]
	v_mov_b64_e32 v[10:11], v[14:15]
	v_lshl_add_u64 v[34:35], v[34:35], 0, s[4:5]
	v_mov_b64_e32 v[22:23], v[18:19]
	v_mov_b64_e32 v[12:13], v[16:17]
	s_andn2_b64 exec, exec, s[8:9]
	s_cbranch_execz .LBB0_465

.LBB0_1466:
	s_or_b64 exec, exec, s[4:5]
	v_lshlrev_b32_e32 v52, 16, v28
	v_and_b32_e32 v53, 0xffff0000, v28
	v_pk_mul_f32 v[54:55], v[52:53], v[52:53]
	v_lshlrev_b32_e32 v28, 16, v29
	v_and_b32_e32 v29, 0xffff0000, v29
	v_pk_mul_f32 v[56:57], v[28:29], v[28:29]
	v_add_f32_e32 v40, v54, v55
	v_lshlrev_b32_e32 v58, 16, v30
	v_and_b32_e32 v59, 0xffff0000, v30
	v_add_f32_e32 v40, v56, v40
	v_pk_mul_f32 v[60:61], v[58:59], v[58:59]
	v_add_f32_e32 v40, v57, v40
	v_lshlrev_b32_e32 v30, 16, v31
	v_and_b32_e32 v31, 0xffff0000, v31
	v_add_f32_e32 v40, v60, v40
	v_pk_mul_f32 v[62:63], v[30:31], v[30:31]
	v_add_f32_e32 v40, v61, v40
	v_lshlrev_b32_e32 v64, 16, v24
	v_and_b32_e32 v65, 0xffff0000, v24
	v_add_f32_e32 v40, v62, v40
	v_pk_mul_f32 v[66:67], v[64:65], v[64:65]
	v_add_f32_e32 v40, v63, v40
	v_lshlrev_b32_e32 v68, 16, v25
	v_and_b32_e32 v69, 0xffff0000, v25
	v_add_f32_e32 v40, v66, v40
	v_pk_mul_f32 v[24:25], v[68:69], v[68:69]
	v_add_f32_e32 v40, v67, v40
	v_lshlrev_b32_e32 v70, 16, v26
	v_and_b32_e32 v71, 0xffff0000, v26
	v_add_f32_e32 v24, v24, v40
	v_lshlrev_b32_e32 v72, 16, v27
	v_and_b32_e32 v73, 0xffff0000, v27
	v_pk_mul_f32 v[26:27], v[70:71], v[70:71]
	v_add_f32_e32 v24, v25, v24
	v_add_f32_e32 v24, v26, v24
	v_pk_mul_f32 v[74:75], v[72:73], v[72:73]
	v_add_f32_e32 v24, v27, v24
	v_add_f32_e32 v24, v74, v24
	v_add_f32_e32 v24, v75, v24
	s_nop 0
	v_lshl_add_u64 v[54:55], v[32:33], 0, v[34:35]
	s_and_b64 s[0:1], exec, s[0:1]
	s_or_b64 s[2:3], s[0:1], s[2:3]
	v_lshl_add_u64 v[32:33], v[32:33], 0, s[6:7]
	s_nop 0
	s_nop 0
	s_nop 0
	s_nop 0
	s_nop 0
	s_nop 0
	s_nop 0
	s_nop 0
	s_nop 0
	s_nop 0
	s_nop 0
	s_nop 0
	s_nop 0
	s_nop 0
	s_nop 0
	s_nop 0
	s_nop 1
	v_add_f32_dpp v25, v24, v24 quad_perm:[1,0,3,2] row_mask:0xf bank_mask:0xf
	s_nop 1
	v_add_f32_dpp v25, v25, v25 quad_perm:[2,3,0,1] row_mask:0xf bank_mask:0xf
	s_nop 1
	v_add_f32_dpp v25, v25, v25 row_half_mirror row_mask:0xf bank_mask:0xf
	s_nop 1
	v_add_f32_dpp v25, v25, v25 row_mirror row_mask:0xf bank_mask:0xf
	s_nop 1
	v_readlane_b32 s60, v25, 0
	v_readlane_b32 s61, v25, 16
	v_readlane_b32 s62, v25, 32
	v_readlane_b32 s63, v25, 48
	s_nop 2
	v_mov_b32_e32 v24, s60
	v_add_f32_e32 v24, s61, v24
	v_add_f32_e32 v24, s62, v24
	v_add_f32_e32 v24, s63, v24
	v_fmamk_f32 v24, v24, 0x3a800000, v41
	v_mul_f32_e32 v25, 0x4b800000, v24
	v_cmp_gt_f32_e32 vcc, s8, v24
	s_nop 1
	v_cndmask_b32_e32 v24, v24, v25, vcc
	v_rsq_f32_e32 v24, v24
	s_nop 0
	v_mul_f32_e32 v25, 0x45800000, v24
	v_cndmask_b32_e32 v40, v24, v25, vcc
	v_pk_mul_f32 v[24:25], v[40:41], v[52:53] op_sel_hi:[0,1]
	v_pk_mul_f32 v[26:27], v[40:41], v[28:29] op_sel_hi:[0,1]
	s_waitcnt vmcnt(2)
	v_pk_mul_f32 v[26:27], v[6:7], v[26:27]
	v_pk_mul_f32 v[24:25], v[4:5], v[24:25]
	global_store_dwordx4 v[54:55], v[24:27], off
	s_nop 1
	v_pk_mul_f32 v[24:25], v[40:41], v[58:59] op_sel_hi:[0,1]
	v_pk_mul_f32 v[26:27], v[40:41], v[30:31] op_sel_hi:[0,1]
	v_pk_mul_f32 v[26:27], v[2:3], v[26:27]
	v_pk_mul_f32 v[24:25], v[0:1], v[24:25]
	global_store_dwordx4 v[54:55], v[24:27], off offset:16
	s_waitcnt vmcnt(3)
	v_mov_b64_e32 v[30:31], v[22:23]
	v_mov_b64_e32 v[28:29], v[20:21]
	v_pk_mul_f32 v[24:25], v[40:41], v[64:65] op_sel_hi:[0,1]
	v_pk_mul_f32 v[26:27], v[40:41], v[68:69] op_sel_hi:[0,1]
	s_waitcnt vmcnt(2)
	v_pk_mul_f32 v[26:27], v[14:15], v[26:27]
	v_pk_mul_f32 v[24:25], v[12:13], v[24:25]
	global_store_dwordx4 v[54:55], v[24:27], off offset:2048
	s_nop 1
	v_pk_mul_f32 v[24:25], v[40:41], v[70:71] op_sel_hi:[0,1]
	v_pk_mul_f32 v[26:27], v[40:41], v[72:73] op_sel_hi:[0,1]
	v_pk_mul_f32 v[26:27], v[10:11], v[26:27]
	v_pk_mul_f32 v[24:25], v[8:9], v[24:25]
	global_store_dwordx4 v[54:55], v[24:27], off offset:2064
	v_mov_b32_e32 v40, v50
	s_nop 0
	v_mov_b64_e32 v[26:27], v[18:19]
	v_mov_b64_e32 v[24:25], v[16:17]
	s_andn2_b64 exec, exec, s[2:3]
	s_cbranch_execz .LBB0_1471
